# speedup vs baseline: 1.0061x; 1.0061x over previous
.LBB0_354:
	v_mov_b32_e32 v134, v252
	s_movk_i32 s1, 0x1800
	v_and_b32_e32 v135, 15, v134
	v_ashrrev_i32_e32 v139, 2, v134
	v_lshlrev_b32_e32 v134, 3, v134
	v_and_b32_e32 v140, 24, v134
	v_and_b32_e32 v134, -4, v139
	v_lshl_add_u32 v143, v134, 2, s54
	ds_read_b128 v[144:147], v143
	v_lshl_add_u32 v138, v135, 2, s26
	v_mul_lo_u32 v135, v139, s94
	v_lshlrev_b32_e32 v141, 2, v140
	v_add3_u32 v141, s26, v135, v141
	v_add_u32_e32 v142, s16, v139
	v_mad_u64_u32 v[134:135], s[16:17], v134, s94, v[138:139]
	s_waitcnt lgkmcnt(0)
	v_mul_f32_e32 v122, v122, v144
	ds_write_b32 v134, v122
	v_mul_f32_e32 v122, v126, v144
	ds_write_b32 v134, v122 offset:64
	v_mul_f32_e32 v122, v123, v145
	ds_write_b32 v134, v122 offset:144
	v_mul_f32_e32 v122, v127, v145
	ds_write_b32 v134, v122 offset:208
	v_mul_f32_e32 v122, v124, v146
	ds_write_b32 v134, v122 offset:288
	v_mul_f32_e32 v122, v128, v146
	ds_write_b32 v134, v122 offset:352
	v_or_b32_e32 v122, 3, v139
	v_mad_u64_u32 v[122:123], s[16:17], v122, s94, v[138:139]
	v_mul_f32_e32 v123, v125, v147
	ds_write_b32 v122, v123
	v_mul_f32_e32 v123, v129, v147
	ds_write_b32 v122, v123 offset:64
	ds_read_b128 v[124:127], v141
	ds_read_b128 v[148:151], v141 offset:16
	v_mul_f32_e32 v114, v114, v144
	ds_write_b32 v134, v114
	v_mul_f32_e32 v114, v118, v144
	ds_write_b32 v134, v114 offset:64
	v_mul_f32_e32 v114, v115, v145
	v_add_u32_e32 v156, s46, v142
	s_waitcnt lgkmcnt(0)
	v_cvt_pk_bf16_f32 v152, v124, v125
	v_mov_b64_e32 v[124:125], s[6:7]
	ds_write_b32 v134, v114 offset:144
	v_mul_f32_e32 v114, v119, v145
	v_cvt_pk_bf16_f32 v153, v126, v127
	v_mad_i64_i32 v[126:127], s[16:17], v156, s1, v[124:125]
	s_lshl_b64 s[12:13], s[12:13], 1
	ds_write_b32 v134, v114 offset:208
	v_mul_f32_e32 v114, v116, v146
	v_lshl_add_u64 v[126:127], v[126:127], 0, s[12:13]
	ds_write_b32 v134, v114 offset:288
	v_mul_f32_e32 v114, v120, v146
	v_lshl_add_u64 v[128:129], v[126:127], 0, s[74:75]
	v_lshlrev_b32_e32 v126, 1, v140
	v_mov_b32_e32 v127, v0
	ds_write_b32 v134, v114 offset:352
	v_mul_f32_e32 v114, v117, v147
	v_lshl_add_u64 v[128:129], v[128:129], 0, v[126:127]
	ds_write_b32 v122, v114
	v_mul_f32_e32 v114, v121, v147
	v_cvt_pk_bf16_f32 v154, v148, v149
	v_cvt_pk_bf16_f32 v155, v150, v151
	global_store_dwordx4 v[128:129], v[152:155], off nt
	ds_write_b32 v122, v114 offset:64
	ds_read_b128 v[114:117], v141
	ds_read_b128 v[118:121], v141 offset:16
	s_waitcnt lgkmcnt(0)
	v_cvt_pk_bf16_f32 v114, v114, v115
	v_cvt_pk_bf16_f32 v115, v116, v117
	v_cvt_pk_bf16_f32 v116, v118, v119
	v_cvt_pk_bf16_f32 v117, v120, v121
	global_store_dwordx4 v[128:129], v[114:117], off offset:256 nt
	ds_read_b128 v[114:117], v143 offset:64
	v_add_u32_e32 v118, s47, v142
	s_and_b64 vcc, exec, s[14:15]
	s_waitcnt lgkmcnt(0)
	v_mul_f32_e32 v106, v106, v114
	ds_write_b32 v134, v106
	v_mul_f32_e32 v106, v110, v114
	ds_write_b32 v134, v106 offset:64
	v_mul_f32_e32 v106, v107, v115
	ds_write_b32 v134, v106 offset:144
	v_mul_f32_e32 v106, v111, v115
	ds_write_b32 v134, v106 offset:208
	v_mul_f32_e32 v106, v108, v116
	ds_write_b32 v134, v106 offset:288
	v_mul_f32_e32 v106, v112, v116
	ds_write_b32 v134, v106 offset:352
	v_mul_f32_e32 v106, v109, v117
	ds_write_b32 v122, v106
	v_mul_f32_e32 v106, v113, v117
	ds_write_b32 v122, v106 offset:64
	ds_read_b128 v[106:109], v141
	ds_read_b128 v[110:113], v141 offset:16
	v_mul_f32_e32 v98, v98, v114
	ds_write_b32 v134, v98
	v_mul_f32_e32 v98, v102, v114
	ds_write_b32 v134, v98 offset:64
	v_mul_f32_e32 v98, v99, v115
	ds_write_b32 v134, v98 offset:144
	v_mul_f32_e32 v98, v103, v115
	s_waitcnt lgkmcnt(0)
	v_cvt_pk_bf16_f32 v106, v106, v107
	v_cvt_pk_bf16_f32 v107, v108, v109
	v_cvt_pk_bf16_f32 v108, v110, v111
	v_mad_i64_i32 v[110:111], s[16:17], v118, s1, v[124:125]
	ds_write_b32 v134, v98 offset:208
	v_mul_f32_e32 v98, v100, v116
	v_lshl_add_u64 v[110:111], v[110:111], 0, s[12:13]
	ds_write_b32 v134, v98 offset:288
	v_mul_f32_e32 v98, v104, v116
	v_lshl_add_u64 v[110:111], v[110:111], 0, s[74:75]
	ds_write_b32 v134, v98 offset:352
	v_mul_f32_e32 v98, v101, v117
	v_lshl_add_u64 v[110:111], v[110:111], 0, v[126:127]
	ds_write_b32 v122, v98
	v_mul_f32_e32 v98, v105, v117
	v_cvt_pk_bf16_f32 v109, v112, v113
	global_store_dwordx4 v[110:111], v[106:109], off nt
	ds_write_b32 v122, v98 offset:64
	ds_read_b128 v[98:101], v141
	ds_read_b128 v[102:105], v141 offset:16
	s_waitcnt lgkmcnt(0)
	v_cvt_pk_bf16_f32 v98, v98, v99
	v_cvt_pk_bf16_f32 v99, v100, v101
	v_cvt_pk_bf16_f32 v100, v102, v103
	v_cvt_pk_bf16_f32 v101, v104, v105
	global_store_dwordx4 v[110:111], v[98:101], off offset:256 nt
	ds_read_b128 v[98:101], v143 offset:128
	v_add_u32_e32 v102, s48, v142
	s_waitcnt lgkmcnt(0)
	v_mul_f32_e32 v90, v90, v98
	ds_write_b32 v134, v90
	v_mul_f32_e32 v90, v94, v98
	ds_write_b32 v134, v90 offset:64
	v_mul_f32_e32 v90, v91, v99
	ds_write_b32 v134, v90 offset:144
	v_mul_f32_e32 v90, v95, v99
	ds_write_b32 v134, v90 offset:208
	v_mul_f32_e32 v90, v92, v100
	ds_write_b32 v134, v90 offset:288
	v_mul_f32_e32 v90, v96, v100
	ds_write_b32 v134, v90 offset:352
	v_mul_f32_e32 v90, v93, v101
	ds_write_b32 v122, v90
	v_mul_f32_e32 v90, v97, v101
	ds_write_b32 v122, v90 offset:64
	ds_read_b128 v[90:93], v141
	ds_read_b128 v[94:97], v141 offset:16
	v_mul_f32_e32 v82, v82, v98
	ds_write_b32 v134, v82
	v_mul_f32_e32 v82, v86, v98
	ds_write_b32 v134, v82 offset:64
	v_mul_f32_e32 v82, v83, v99
	ds_write_b32 v134, v82 offset:144
	v_mul_f32_e32 v82, v87, v99
	s_waitcnt lgkmcnt(0)
	v_cvt_pk_bf16_f32 v90, v90, v91
	v_cvt_pk_bf16_f32 v91, v92, v93
	v_cvt_pk_bf16_f32 v92, v94, v95
	v_mad_i64_i32 v[94:95], s[16:17], v102, s1, v[124:125]
	ds_write_b32 v134, v82 offset:208
	v_mul_f32_e32 v82, v84, v100
	v_lshl_add_u64 v[94:95], v[94:95], 0, s[12:13]
	ds_write_b32 v134, v82 offset:288
	v_mul_f32_e32 v82, v88, v100
	v_lshl_add_u64 v[94:95], v[94:95], 0, s[74:75]
	ds_write_b32 v134, v82 offset:352
	v_mul_f32_e32 v82, v85, v101
	v_lshl_add_u64 v[94:95], v[94:95], 0, v[126:127]
	ds_write_b32 v122, v82
	v_mul_f32_e32 v82, v89, v101
	v_cvt_pk_bf16_f32 v93, v96, v97
	global_store_dwordx4 v[94:95], v[90:93], off nt
	ds_write_b32 v122, v82 offset:64
	ds_read_b128 v[82:85], v141
	ds_read_b128 v[86:89], v141 offset:16
	s_waitcnt lgkmcnt(0)
	v_cvt_pk_bf16_f32 v82, v82, v83
	v_cvt_pk_bf16_f32 v83, v84, v85
	v_cvt_pk_bf16_f32 v84, v86, v87
	v_cvt_pk_bf16_f32 v85, v88, v89
	global_store_dwordx4 v[94:95], v[82:85], off offset:256 nt
	ds_read_b128 v[82:85], v143 offset:192
	v_add_u32_e32 v86, s49, v142
	s_waitcnt lgkmcnt(0)
	v_mul_f32_e32 v74, v74, v82
	ds_write_b32 v134, v74
	v_mul_f32_e32 v74, v78, v82
	ds_write_b32 v134, v74 offset:64
	v_mul_f32_e32 v74, v75, v83
	ds_write_b32 v134, v74 offset:144
	v_mul_f32_e32 v74, v79, v83
	ds_write_b32 v134, v74 offset:208
	v_mul_f32_e32 v74, v76, v84
	ds_write_b32 v134, v74 offset:288
	v_mul_f32_e32 v74, v80, v84
	ds_write_b32 v134, v74 offset:352
	v_mul_f32_e32 v74, v77, v85
	ds_write_b32 v122, v74
	v_mul_f32_e32 v74, v81, v85
	ds_write_b32 v122, v74 offset:64
	ds_read_b128 v[74:77], v141
	ds_read_b128 v[78:81], v141 offset:16
	v_mul_f32_e32 v66, v66, v82
	ds_write_b32 v134, v66
	v_mul_f32_e32 v66, v70, v82
	ds_write_b32 v134, v66 offset:64
	v_mul_f32_e32 v66, v67, v83
	ds_write_b32 v134, v66 offset:144
	v_mul_f32_e32 v66, v71, v83
	s_waitcnt lgkmcnt(0)
	v_cvt_pk_bf16_f32 v74, v74, v75
	v_cvt_pk_bf16_f32 v75, v76, v77
	v_cvt_pk_bf16_f32 v76, v78, v79
	v_mad_i64_i32 v[78:79], s[16:17], v86, s1, v[124:125]
	ds_write_b32 v134, v66 offset:208
	v_mul_f32_e32 v66, v68, v84
	v_lshl_add_u64 v[78:79], v[78:79], 0, s[12:13]
	ds_write_b32 v134, v66 offset:288
	v_mul_f32_e32 v66, v72, v84
	v_lshl_add_u64 v[78:79], v[78:79], 0, s[74:75]
	ds_write_b32 v134, v66 offset:352
	v_mul_f32_e32 v66, v69, v85
	v_lshl_add_u64 v[78:79], v[78:79], 0, v[126:127]
	ds_write_b32 v122, v66
	v_mul_f32_e32 v66, v73, v85
	v_cvt_pk_bf16_f32 v77, v80, v81
	global_store_dwordx4 v[78:79], v[74:77], off nt
	ds_write_b32 v122, v66 offset:64
	ds_read_b128 v[66:69], v141
	ds_read_b128 v[70:73], v141 offset:16
	s_waitcnt lgkmcnt(0)
	v_cvt_pk_bf16_f32 v66, v66, v67
	v_cvt_pk_bf16_f32 v67, v68, v69
	v_cvt_pk_bf16_f32 v68, v70, v71
	v_cvt_pk_bf16_f32 v69, v72, v73
	global_store_dwordx4 v[78:79], v[66:69], off offset:256 nt
	ds_read_b128 v[66:69], v143 offset:512
	v_add_u32_e32 v70, s50, v142
	s_waitcnt lgkmcnt(0)
	v_mul_f32_e32 v58, v58, v66
	ds_write_b32 v134, v58
	v_mul_f32_e32 v58, v62, v66
	ds_write_b32 v134, v58 offset:64
	v_mul_f32_e32 v58, v59, v67
	ds_write_b32 v134, v58 offset:144
	v_mul_f32_e32 v58, v63, v67
	ds_write_b32 v134, v58 offset:208
	v_mul_f32_e32 v58, v60, v68
	ds_write_b32 v134, v58 offset:288
	v_mul_f32_e32 v58, v64, v68
	ds_write_b32 v134, v58 offset:352
	v_mul_f32_e32 v58, v61, v69
	ds_write_b32 v122, v58
	v_mul_f32_e32 v58, v65, v69
	ds_write_b32 v122, v58 offset:64
	ds_read_b128 v[58:61], v141
	ds_read_b128 v[62:65], v141 offset:16
	v_mul_f32_e32 v50, v50, v66
	ds_write_b32 v134, v50
	v_mul_f32_e32 v50, v54, v66
	ds_write_b32 v134, v50 offset:64
	v_mul_f32_e32 v50, v51, v67
	ds_write_b32 v134, v50 offset:144
	v_mul_f32_e32 v50, v55, v67
	s_waitcnt lgkmcnt(0)
	v_cvt_pk_bf16_f32 v58, v58, v59
	v_cvt_pk_bf16_f32 v59, v60, v61
	v_cvt_pk_bf16_f32 v60, v62, v63
	v_mad_i64_i32 v[62:63], s[16:17], v70, s1, v[124:125]
	ds_write_b32 v134, v50 offset:208
	v_mul_f32_e32 v50, v52, v68
	v_lshl_add_u64 v[62:63], v[62:63], 0, s[12:13]
	ds_write_b32 v134, v50 offset:288
	v_mul_f32_e32 v50, v56, v68
	v_lshl_add_u64 v[62:63], v[62:63], 0, s[74:75]
	ds_write_b32 v134, v50 offset:352
	v_mul_f32_e32 v50, v53, v69
	v_lshl_add_u64 v[62:63], v[62:63], 0, v[126:127]
	ds_write_b32 v122, v50
	v_mul_f32_e32 v50, v57, v69
	v_cvt_pk_bf16_f32 v61, v64, v65
	global_store_dwordx4 v[62:63], v[58:61], off nt
	ds_write_b32 v122, v50 offset:64
	ds_read_b128 v[50:53], v141
	ds_read_b128 v[54:57], v141 offset:16
	s_waitcnt lgkmcnt(0)
	v_cvt_pk_bf16_f32 v50, v50, v51
	v_cvt_pk_bf16_f32 v51, v52, v53
	v_cvt_pk_bf16_f32 v52, v54, v55
	v_cvt_pk_bf16_f32 v53, v56, v57
	global_store_dwordx4 v[62:63], v[50:53], off offset:256 nt
	ds_read_b128 v[50:53], v143 offset:576
	v_add_u32_e32 v54, s51, v142
	s_waitcnt lgkmcnt(0)
	v_mul_f32_e32 v42, v42, v50
	ds_write_b32 v134, v42
	v_mul_f32_e32 v42, v46, v50
	ds_write_b32 v134, v42 offset:64
	v_mul_f32_e32 v42, v43, v51
	ds_write_b32 v134, v42 offset:144
	v_mul_f32_e32 v42, v47, v51
	ds_write_b32 v134, v42 offset:208
	v_mul_f32_e32 v42, v44, v52
	ds_write_b32 v134, v42 offset:288
	v_mul_f32_e32 v42, v48, v52
	ds_write_b32 v134, v42 offset:352
	v_mul_f32_e32 v42, v45, v53
	ds_write_b32 v122, v42
	v_mul_f32_e32 v42, v49, v53
	ds_write_b32 v122, v42 offset:64
	ds_read_b128 v[42:45], v141
	ds_read_b128 v[46:49], v141 offset:16
	v_mul_f32_e32 v34, v34, v50
	ds_write_b32 v134, v34
	v_mul_f32_e32 v34, v38, v50
	ds_write_b32 v134, v34 offset:64
	v_mul_f32_e32 v34, v35, v51
	ds_write_b32 v134, v34 offset:144
	v_mul_f32_e32 v34, v39, v51
	s_waitcnt lgkmcnt(0)
	v_cvt_pk_bf16_f32 v42, v42, v43
	v_cvt_pk_bf16_f32 v43, v44, v45
	v_cvt_pk_bf16_f32 v44, v46, v47
	v_mad_i64_i32 v[46:47], s[16:17], v54, s1, v[124:125]
	ds_write_b32 v134, v34 offset:208
	v_mul_f32_e32 v34, v36, v52
	v_lshl_add_u64 v[46:47], v[46:47], 0, s[12:13]
	ds_write_b32 v134, v34 offset:288
	v_mul_f32_e32 v34, v40, v52
	v_lshl_add_u64 v[46:47], v[46:47], 0, s[74:75]
	ds_write_b32 v134, v34 offset:352
	v_mul_f32_e32 v34, v37, v53
	v_lshl_add_u64 v[46:47], v[46:47], 0, v[126:127]
	ds_write_b32 v122, v34
	v_mul_f32_e32 v34, v41, v53
	v_cvt_pk_bf16_f32 v45, v48, v49
	global_store_dwordx4 v[46:47], v[42:45], off nt
	ds_write_b32 v122, v34 offset:64
	ds_read_b128 v[34:37], v141
	ds_read_b128 v[38:41], v141 offset:16
	s_waitcnt lgkmcnt(0)
	v_cvt_pk_bf16_f32 v34, v34, v35
	v_cvt_pk_bf16_f32 v35, v36, v37
	v_cvt_pk_bf16_f32 v36, v38, v39
	v_cvt_pk_bf16_f32 v37, v40, v41
	global_store_dwordx4 v[46:47], v[34:37], off offset:256 nt
	ds_read_b128 v[34:37], v143 offset:640
	v_add_u32_e32 v38, s52, v142
	s_waitcnt lgkmcnt(0)
	v_mul_f32_e32 v26, v26, v34
	ds_write_b32 v134, v26
	v_mul_f32_e32 v26, v30, v34
	ds_write_b32 v134, v26 offset:64
	v_mul_f32_e32 v26, v27, v35
	ds_write_b32 v134, v26 offset:144
	v_mul_f32_e32 v26, v31, v35
	ds_write_b32 v134, v26 offset:208
	v_mul_f32_e32 v26, v28, v36
	ds_write_b32 v134, v26 offset:288
	v_mul_f32_e32 v26, v32, v36
	ds_write_b32 v134, v26 offset:352
	v_mul_f32_e32 v26, v29, v37
	ds_write_b32 v122, v26
	v_mul_f32_e32 v26, v33, v37
	ds_write_b32 v122, v26 offset:64
	ds_read_b128 v[26:29], v141
	ds_read_b128 v[30:33], v141 offset:16
	v_mul_f32_e32 v18, v18, v34
	ds_write_b32 v134, v18
	v_mul_f32_e32 v18, v22, v34
	ds_write_b32 v134, v18 offset:64
	v_mul_f32_e32 v18, v19, v35
	ds_write_b32 v134, v18 offset:144
	v_mul_f32_e32 v18, v23, v35
	s_waitcnt lgkmcnt(0)
	v_cvt_pk_bf16_f32 v26, v26, v27
	v_cvt_pk_bf16_f32 v27, v28, v29
	v_cvt_pk_bf16_f32 v28, v30, v31
	v_mad_i64_i32 v[30:31], s[16:17], v38, s1, v[124:125]
	ds_write_b32 v134, v18 offset:208
	v_mul_f32_e32 v18, v20, v36
	v_lshl_add_u64 v[30:31], v[30:31], 0, s[12:13]
	ds_write_b32 v134, v18 offset:288
	v_mul_f32_e32 v18, v24, v36
	v_lshl_add_u64 v[30:31], v[30:31], 0, s[74:75]
	ds_write_b32 v134, v18 offset:352
	v_mul_f32_e32 v18, v21, v37
	v_lshl_add_u64 v[30:31], v[30:31], 0, v[126:127]
	ds_write_b32 v122, v18
	v_mul_f32_e32 v18, v25, v37
	v_cvt_pk_bf16_f32 v29, v32, v33
	global_store_dwordx4 v[30:31], v[26:29], off nt
	ds_write_b32 v122, v18 offset:64
	ds_read_b128 v[18:21], v141
	ds_read_b128 v[22:25], v141 offset:16
	s_waitcnt lgkmcnt(0)
	v_cvt_pk_bf16_f32 v18, v18, v19
	v_cvt_pk_bf16_f32 v19, v20, v21
	v_cvt_pk_bf16_f32 v20, v22, v23
	v_cvt_pk_bf16_f32 v21, v24, v25
	global_store_dwordx4 v[30:31], v[18:21], off offset:256 nt
	ds_read_b128 v[18:21], v143 offset:704
	v_add_u32_e32 v22, s53, v142
	s_waitcnt lgkmcnt(0)
	v_mul_f32_e32 v10, v10, v18
	ds_write_b32 v134, v10
	v_mul_f32_e32 v10, v14, v18
	ds_write_b32 v134, v10 offset:64
	v_mul_f32_e32 v10, v11, v19
	ds_write_b32 v134, v10 offset:144
	v_mul_f32_e32 v10, v15, v19
	ds_write_b32 v134, v10 offset:208
	v_mul_f32_e32 v10, v12, v20
	ds_write_b32 v134, v10 offset:288
	v_mul_f32_e32 v10, v16, v20
	ds_write_b32 v134, v10 offset:352
	v_mul_f32_e32 v10, v13, v21
	ds_write_b32 v122, v10
	v_mul_f32_e32 v10, v17, v21
	ds_write_b32 v122, v10 offset:64
	ds_read_b128 v[10:13], v141
	ds_read_b128 v[14:17], v141 offset:16
	v_mul_f32_e32 v2, v2, v18
	ds_write_b32 v134, v2
	v_mul_f32_e32 v2, v6, v18
	ds_write_b32 v134, v2 offset:64
	v_mul_f32_e32 v2, v3, v19
	ds_write_b32 v134, v2 offset:144
	v_mul_f32_e32 v2, v7, v19
	s_waitcnt lgkmcnt(0)
	v_cvt_pk_bf16_f32 v10, v10, v11
	v_cvt_pk_bf16_f32 v11, v12, v13
	v_cvt_pk_bf16_f32 v12, v14, v15
	v_mad_i64_i32 v[14:15], s[16:17], v22, s1, v[124:125]
	ds_write_b32 v134, v2 offset:208
	v_mul_f32_e32 v2, v4, v20
	v_lshl_add_u64 v[14:15], v[14:15], 0, s[12:13]
	ds_write_b32 v134, v2 offset:288
	v_mul_f32_e32 v2, v8, v20
	v_lshl_add_u64 v[14:15], v[14:15], 0, s[74:75]
	ds_write_b32 v134, v2 offset:352
	v_mul_f32_e32 v2, v5, v21
	v_lshl_add_u64 v[14:15], v[14:15], 0, v[126:127]
	ds_write_b32 v122, v2
	v_mul_f32_e32 v2, v9, v21
	v_cvt_pk_bf16_f32 v13, v16, v17
	global_store_dwordx4 v[14:15], v[10:13], off nt
	ds_write_b32 v122, v2 offset:64
	ds_read_b128 v[2:5], v141
	ds_read_b128 v[6:9], v141 offset:16
	s_waitcnt lgkmcnt(0)
	v_cvt_pk_bf16_f32 v2, v2, v3
	v_cvt_pk_bf16_f32 v3, v4, v5
	v_cvt_pk_bf16_f32 v4, v6, v7
	v_cvt_pk_bf16_f32 v5, v8, v9
	global_store_dwordx4 v[14:15], v[2:5], off offset:256 nt
	s_waitcnt vmcnt(32)
	v_add_f32_e32 v164, v160, v161
	v_add_f32_e32 v164, v162, v164
	v_add_f32_e32 v164, v163, v164
	v_fmamk_f32 v164, v164, 0x3a800000, v208
	v_mul_f32_e32 v165, 0x4b800000, v164
	v_cmp_gt_f32_e64 s[12:13], s95, v164
	s_nop 1
	v_cndmask_b32_e64 v164, v164, v165, s[12:13]
	v_rsq_f32_e32 v164, v164
	s_nop 0
	v_mul_f32_e32 v165, 0x45800000, v164
	v_cndmask_b32_e64 v206, v164, v165, s[12:13]
	s_barrier
	s_cbranch_vccnz .LBB0_370

.LBB0_458:
	v_mov_b32_e32 v134, v253
	s_movk_i32 s18, 0x1600
	v_and_b32_e32 v135, 15, v134
	v_ashrrev_i32_e32 v139, 2, v134
	v_lshlrev_b32_e32 v134, 3, v134
	v_and_b32_e32 v140, 24, v134
	v_and_b32_e32 v134, -4, v139
	v_lshl_add_u32 v142, v134, 2, s48
	ds_read_b128 v[144:147], v142
	v_lshl_add_u32 v138, v135, 2, s24
	v_mul_lo_u32 v135, v139, s94
	v_lshlrev_b32_e32 v141, 2, v140
	v_add3_u32 v141, s24, v135, v141
	s_waitcnt lgkmcnt(0)
	v_mul_f32_e32 v143, 0xbfb8aa3b, v144
	v_mul_f32_e32 v135, v118, v143
	v_exp_f32_e32 v152, v135
	v_mad_u64_u32 v[134:135], s[16:17], v134, s94, v[138:139]
	v_mul_f32_e32 v118, v118, v126
	v_add_f32_e32 v135, 1.0, v152
	v_rcp_f32_e32 v135, v135
	v_mul_f32_e32 v126, v114, v143
	v_exp_f32_e32 v126, v126
	v_pk_mul_f32 v[150:151], v[144:145], v[144:145]
	v_mul_f32_e32 v114, v114, v122
	v_mul_f32_e32 v135, v150, v135
	v_mul_f32_e32 v118, v118, v135
	ds_write_b32 v134, v118
	v_add_f32_e32 v118, 1.0, v126
	v_rcp_f32_e32 v118, v118
	v_mul_f32_e32 v122, 0xbfb8aa3b, v145
	v_mul_f32_e32 v126, v119, v122
	v_exp_f32_e32 v126, v126
	v_mul_f32_e32 v118, v150, v118
	v_mul_f32_e32 v114, v114, v118
	ds_write_b32 v134, v114 offset:64
	v_add_f32_e32 v114, 1.0, v126
	v_rcp_f32_e32 v114, v114
	v_mul_f32_e32 v118, v119, v127
	v_mul_f32_e32 v119, v115, v122
	v_exp_f32_e32 v119, v119
	v_mul_f32_e32 v114, v151, v114
	v_mul_f32_e32 v114, v118, v114
	ds_write_b32 v134, v114 offset:144
	v_add_f32_e32 v114, 1.0, v119
	v_mul_f32_e32 v118, 0xbfb8aa3b, v146
	v_rcp_f32_e32 v114, v114
	v_mul_f32_e32 v119, v120, v118
	v_exp_f32_e32 v119, v119
	v_mul_f32_e32 v118, v116, v118
	v_mul_f32_e32 v115, v115, v123
	v_mul_f32_e32 v114, v151, v114
	v_exp_f32_e32 v118, v118
	v_mul_f32_e32 v114, v115, v114
	v_add_f32_e32 v115, 1.0, v119
	v_rcp_f32_e32 v115, v115
	v_add_f32_e32 v118, 1.0, v118
	v_pk_mul_f32 v[148:149], v[146:147], v[146:147]
	v_rcp_f32_e32 v118, v118
	ds_write_b32 v134, v114 offset:208
	v_mul_f32_e32 v114, v120, v128
	v_mul_f32_e32 v115, v148, v115
	v_mul_f32_e32 v114, v114, v115
	ds_write_b32 v134, v114 offset:288
	v_mul_f32_e32 v114, v116, v124
	v_mul_f32_e32 v116, 0xbfb8aa3b, v147
	v_mul_f32_e32 v115, v148, v118
	v_mul_f32_e32 v118, v121, v116
	v_exp_f32_e32 v118, v118
	v_mul_f32_e32 v114, v114, v115
	ds_write_b32 v134, v114 offset:352
	v_or_b32_e32 v114, 3, v139
	v_add_f32_e32 v115, 1.0, v118
	v_rcp_f32_e32 v118, v115
	v_mul_f32_e32 v115, v117, v116
	v_exp_f32_e32 v116, v115
	v_mad_u64_u32 v[114:115], s[16:17], v114, s94, v[138:139]
	v_mul_f32_e32 v115, v121, v129
	v_add_f32_e32 v116, 1.0, v116
	v_rcp_f32_e32 v116, v116
	v_mul_f32_e32 v118, v149, v118
	v_mul_f32_e32 v115, v115, v118
	ds_write_b32 v114, v115
	v_mul_f32_e32 v115, v117, v125
	v_mul_f32_e32 v116, v149, v116
	v_mul_f32_e32 v115, v115, v116
	ds_write_b32 v114, v115 offset:64
	ds_read_b128 v[116:119], v141
	ds_read_b128 v[120:123], v141 offset:16
	s_waitcnt lgkmcnt(0)
	v_cvt_pk_bf16_f32 v126, v120, v121
	v_cvt_pk_bf16_f32 v127, v122, v123
	ds_read_b128 v[120:123], v142 offset:64
	v_add_u32_e32 v135, s12, v139
	s_lshl_b32 s12, s50, 7
	s_ashr_i32 s13, s12, 31
	v_cvt_pk_bf16_f32 v124, v116, v117
	v_add_u32_e32 v115, s44, v135
	v_mov_b64_e32 v[116:117], s[6:7]
	v_cvt_pk_bf16_f32 v125, v118, v119
	v_mad_i64_i32 v[118:119], s[16:17], v115, s18, v[116:117]
	s_lshl_b64 s[12:13], s[12:13], 1
	v_lshl_add_u64 v[118:119], v[118:119], 0, s[12:13]
	v_lshl_add_u64 v[128:129], v[118:119], 0, s[74:75]
	s_waitcnt lgkmcnt(0)
	v_mul_f32_e32 v119, 0xbfb8aa3b, v120
	v_mul_f32_e32 v118, v102, v119
	v_exp_f32_e32 v143, v118
	v_pk_mul_f32 v[144:145], v[120:121], v[120:121]
	v_mul_f32_e32 v102, v102, v110
	v_mul_f32_e32 v110, v98, v119
	v_add_f32_e32 v120, 1.0, v143
	v_rcp_f32_e32 v120, v120
	v_exp_f32_e32 v110, v110
	v_mul_f32_e32 v98, v98, v106
	v_mul_f32_e32 v106, 0xbfb8aa3b, v121
	v_mul_f32_e32 v119, v144, v120
	v_mul_f32_e32 v102, v102, v119
	ds_write_b32 v134, v102
	v_add_f32_e32 v102, 1.0, v110
	v_rcp_f32_e32 v102, v102
	v_mul_f32_e32 v110, v103, v106
	v_exp_f32_e32 v110, v110
	v_pk_mul_f32 v[138:139], v[122:123], v[122:123]
	v_mul_f32_e32 v102, v144, v102
	v_mul_f32_e32 v98, v98, v102
	ds_write_b32 v134, v98 offset:64
	v_add_f32_e32 v98, 1.0, v110
	v_rcp_f32_e32 v98, v98
	v_mul_f32_e32 v102, v103, v111
	v_mul_f32_e32 v103, v99, v106
	v_exp_f32_e32 v103, v103
	v_mul_f32_e32 v98, v145, v98
	v_mul_f32_e32 v98, v102, v98
	ds_write_b32 v134, v98 offset:144
	v_add_f32_e32 v98, 1.0, v103
	v_rcp_f32_e32 v98, v98
	v_mul_f32_e32 v102, 0xbfb8aa3b, v122
	v_mul_f32_e32 v103, v104, v102
	v_exp_f32_e32 v103, v103
	v_mul_f32_e32 v99, v99, v107
	v_mul_f32_e32 v98, v145, v98
	v_mul_f32_e32 v98, v99, v98
	ds_write_b32 v134, v98 offset:208
	v_add_f32_e32 v98, 1.0, v103
	v_rcp_f32_e32 v98, v98
	v_mul_f32_e32 v102, v100, v102
	v_exp_f32_e32 v102, v102
	v_mul_f32_e32 v99, v104, v112
	v_mul_f32_e32 v98, v138, v98
	v_mul_f32_e32 v98, v99, v98
	ds_write_b32 v134, v98 offset:288
	v_add_f32_e32 v98, 1.0, v102
	v_mul_f32_e32 v99, 0xbfb8aa3b, v123
	v_rcp_f32_e32 v98, v98
	v_mul_f32_e32 v102, v105, v99
	v_exp_f32_e32 v102, v102
	v_mul_f32_e32 v99, v101, v99
	v_exp_f32_e32 v99, v99
	v_mul_f32_e32 v100, v100, v108
	v_mul_f32_e32 v98, v138, v98
	v_mul_f32_e32 v98, v100, v98
	v_add_f32_e32 v100, 1.0, v102
	v_rcp_f32_e32 v100, v100
	v_add_f32_e32 v99, 1.0, v99
	v_rcp_f32_e32 v99, v99
	ds_write_b32 v134, v98 offset:352
	v_mul_f32_e32 v98, v105, v113
	v_mul_f32_e32 v100, v139, v100
	v_mul_f32_e32 v98, v98, v100
	ds_write_b32 v114, v98
	v_mul_f32_e32 v98, v101, v109
	v_mul_f32_e32 v99, v139, v99
	v_lshlrev_b32_e32 v118, 1, v140
	v_mul_f32_e32 v98, v98, v99
	v_mov_b32_e32 v119, v0
	ds_write_b32 v114, v98 offset:64
	v_lshl_add_u64 v[106:107], v[128:129], 0, v[118:119]
	global_store_dwordx4 v[106:107], v[124:127], off nt
	ds_read_b128 v[106:109], v142 offset:128
	ds_read_b128 v[98:101], v141
	ds_read_b128 v[102:105], v141 offset:16
	s_waitcnt lgkmcnt(0)
	v_cvt_pk_bf16_f32 v98, v98, v99
	v_cvt_pk_bf16_f32 v99, v100, v101
	v_mul_f32_e32 v112, 0xbfb8aa3b, v106
	v_cvt_pk_bf16_f32 v101, v104, v105
	v_mul_f32_e32 v104, v86, v112
	v_exp_f32_e32 v113, v104
	v_pk_mul_f32 v[110:111], v[106:107], v[106:107]
	v_mul_f32_e32 v86, v86, v94
	v_mul_f32_e32 v94, v82, v112
	v_add_f32_e32 v106, 1.0, v113
	v_rcp_f32_e32 v106, v106
	v_exp_f32_e32 v94, v94
	v_mul_f32_e32 v82, v82, v90
	v_mul_f32_e32 v90, 0xbfb8aa3b, v107
	v_mul_f32_e32 v106, v110, v106
	v_mul_f32_e32 v86, v86, v106
	ds_write_b32 v134, v86
	v_add_f32_e32 v86, 1.0, v94
	v_rcp_f32_e32 v86, v86
	v_mul_f32_e32 v94, v87, v90
	v_exp_f32_e32 v94, v94
	v_pk_mul_f32 v[104:105], v[108:109], v[108:109]
	v_mul_f32_e32 v86, v110, v86
	v_mul_f32_e32 v82, v82, v86
	ds_write_b32 v134, v82 offset:64
	v_add_f32_e32 v82, 1.0, v94
	v_rcp_f32_e32 v82, v82
	v_mul_f32_e32 v86, v87, v95
	v_mul_f32_e32 v87, v83, v90
	v_exp_f32_e32 v87, v87
	v_mul_f32_e32 v82, v111, v82
	v_mul_f32_e32 v82, v86, v82
	ds_write_b32 v134, v82 offset:144
	v_add_f32_e32 v82, 1.0, v87
	v_rcp_f32_e32 v82, v82
	v_mul_f32_e32 v86, 0xbfb8aa3b, v108
	v_mul_f32_e32 v87, v88, v86
	v_exp_f32_e32 v87, v87
	v_mul_f32_e32 v83, v83, v91
	v_mul_f32_e32 v82, v111, v82
	v_mul_f32_e32 v82, v83, v82
	ds_write_b32 v134, v82 offset:208
	v_add_f32_e32 v82, 1.0, v87
	v_rcp_f32_e32 v82, v82
	v_mul_f32_e32 v86, v84, v86
	v_exp_f32_e32 v86, v86
	v_mul_f32_e32 v83, v88, v96
	v_mul_f32_e32 v82, v104, v82
	v_mul_f32_e32 v82, v83, v82
	ds_write_b32 v134, v82 offset:288
	v_add_f32_e32 v82, 1.0, v86
	v_mul_f32_e32 v83, 0xbfb8aa3b, v109
	v_rcp_f32_e32 v82, v82
	v_mul_f32_e32 v86, v89, v83
	v_exp_f32_e32 v86, v86
	v_mul_f32_e32 v83, v85, v83
	v_exp_f32_e32 v83, v83
	v_mul_f32_e32 v84, v84, v92
	v_mul_f32_e32 v82, v104, v82
	v_mul_f32_e32 v82, v84, v82
	v_add_f32_e32 v84, 1.0, v86
	v_rcp_f32_e32 v84, v84
	v_add_f32_e32 v83, 1.0, v83
	v_rcp_f32_e32 v83, v83
	v_cvt_pk_bf16_f32 v100, v102, v103
	v_add_u32_e32 v102, s45, v135
	ds_write_b32 v134, v82 offset:352
	v_mul_f32_e32 v82, v89, v97
	v_mul_f32_e32 v84, v105, v84
	v_mad_i64_i32 v[102:103], s[16:17], v102, s18, v[116:117]
	v_mul_f32_e32 v82, v82, v84
	v_lshl_add_u64 v[102:103], v[102:103], 0, s[12:13]
	ds_write_b32 v114, v82
	v_mul_f32_e32 v82, v85, v93
	v_mul_f32_e32 v83, v105, v83
	v_mul_f32_e32 v82, v82, v83
	v_lshl_add_u64 v[90:91], v[102:103], 0, s[74:75]
	ds_write_b32 v114, v82 offset:64
	v_lshl_add_u64 v[90:91], v[90:91], 0, v[118:119]
	global_store_dwordx4 v[90:91], v[98:101], off nt
	ds_read_b128 v[90:93], v142 offset:192
	ds_read_b128 v[82:85], v141
	ds_read_b128 v[86:89], v141 offset:16
	s_waitcnt lgkmcnt(0)
	v_cvt_pk_bf16_f32 v82, v82, v83
	v_cvt_pk_bf16_f32 v83, v84, v85
	v_mul_f32_e32 v96, 0xbfb8aa3b, v90
	v_cvt_pk_bf16_f32 v85, v88, v89
	v_mul_f32_e32 v88, v70, v96
	v_exp_f32_e32 v97, v88
	v_pk_mul_f32 v[94:95], v[90:91], v[90:91]
	v_mul_f32_e32 v70, v70, v78
	v_mul_f32_e32 v78, v66, v96
	v_add_f32_e32 v90, 1.0, v97
	v_rcp_f32_e32 v90, v90
	v_exp_f32_e32 v78, v78
	v_mul_f32_e32 v66, v66, v74
	v_mul_f32_e32 v74, 0xbfb8aa3b, v91
	v_mul_f32_e32 v90, v94, v90
	v_mul_f32_e32 v70, v70, v90
	ds_write_b32 v134, v70
	v_add_f32_e32 v70, 1.0, v78
	v_rcp_f32_e32 v70, v70
	v_mul_f32_e32 v78, v71, v74
	v_exp_f32_e32 v78, v78
	v_pk_mul_f32 v[88:89], v[92:93], v[92:93]
	v_mul_f32_e32 v70, v94, v70
	v_mul_f32_e32 v66, v66, v70
	ds_write_b32 v134, v66 offset:64
	v_add_f32_e32 v66, 1.0, v78
	v_rcp_f32_e32 v66, v66
	v_mul_f32_e32 v70, v71, v79
	v_mul_f32_e32 v71, v67, v74
	v_exp_f32_e32 v71, v71
	v_mul_f32_e32 v66, v95, v66
	v_mul_f32_e32 v66, v70, v66
	ds_write_b32 v134, v66 offset:144
	v_add_f32_e32 v66, 1.0, v71
	v_rcp_f32_e32 v66, v66
	v_mul_f32_e32 v70, 0xbfb8aa3b, v92
	v_mul_f32_e32 v71, v72, v70
	v_exp_f32_e32 v71, v71
	v_mul_f32_e32 v67, v67, v75
	v_mul_f32_e32 v66, v95, v66
	v_mul_f32_e32 v66, v67, v66
	ds_write_b32 v134, v66 offset:208
	v_add_f32_e32 v66, 1.0, v71
	v_rcp_f32_e32 v66, v66
	v_mul_f32_e32 v70, v68, v70
	v_exp_f32_e32 v70, v70
	v_mul_f32_e32 v67, v72, v80
	v_mul_f32_e32 v66, v88, v66
	v_mul_f32_e32 v66, v67, v66
	ds_write_b32 v134, v66 offset:288
	v_add_f32_e32 v66, 1.0, v70
	v_mul_f32_e32 v67, 0xbfb8aa3b, v93
	v_rcp_f32_e32 v66, v66
	v_mul_f32_e32 v70, v73, v67
	v_exp_f32_e32 v70, v70
	v_mul_f32_e32 v67, v69, v67
	v_exp_f32_e32 v67, v67
	v_mul_f32_e32 v68, v68, v76
	v_mul_f32_e32 v66, v88, v66
	v_mul_f32_e32 v66, v68, v66
	v_add_f32_e32 v68, 1.0, v70
	v_rcp_f32_e32 v68, v68
	v_add_f32_e32 v67, 1.0, v67
	v_rcp_f32_e32 v67, v67
	v_cvt_pk_bf16_f32 v84, v86, v87
	v_add_u32_e32 v86, s46, v135
	ds_write_b32 v134, v66 offset:352
	v_mul_f32_e32 v66, v73, v81
	v_mul_f32_e32 v68, v89, v68
	v_mad_i64_i32 v[86:87], s[16:17], v86, s18, v[116:117]
	v_mul_f32_e32 v66, v66, v68
	v_lshl_add_u64 v[86:87], v[86:87], 0, s[12:13]
	ds_write_b32 v114, v66
	v_mul_f32_e32 v66, v69, v77
	v_mul_f32_e32 v67, v89, v67
	v_mul_f32_e32 v66, v66, v67
	v_lshl_add_u64 v[74:75], v[86:87], 0, s[74:75]
	ds_write_b32 v114, v66 offset:64
	v_lshl_add_u64 v[74:75], v[74:75], 0, v[118:119]
	global_store_dwordx4 v[74:75], v[82:85], off nt
	ds_read_b128 v[74:77], v142 offset:512
	ds_read_b128 v[66:69], v141
	ds_read_b128 v[70:73], v141 offset:16
	s_waitcnt lgkmcnt(0)
	v_cvt_pk_bf16_f32 v66, v66, v67
	v_cvt_pk_bf16_f32 v67, v68, v69
	v_mul_f32_e32 v80, 0xbfb8aa3b, v74
	v_cvt_pk_bf16_f32 v69, v72, v73
	v_mul_f32_e32 v72, v54, v80
	v_exp_f32_e32 v81, v72
	v_pk_mul_f32 v[78:79], v[74:75], v[74:75]
	v_mul_f32_e32 v54, v54, v62
	v_mul_f32_e32 v62, v50, v80
	v_add_f32_e32 v74, 1.0, v81
	v_rcp_f32_e32 v74, v74
	v_exp_f32_e32 v62, v62
	v_mul_f32_e32 v50, v50, v58
	v_mul_f32_e32 v58, 0xbfb8aa3b, v75
	v_mul_f32_e32 v74, v78, v74
	v_mul_f32_e32 v54, v54, v74
	ds_write_b32 v134, v54
	v_add_f32_e32 v54, 1.0, v62
	v_rcp_f32_e32 v54, v54
	v_mul_f32_e32 v62, v55, v58
	v_exp_f32_e32 v62, v62
	v_pk_mul_f32 v[72:73], v[76:77], v[76:77]
	v_mul_f32_e32 v54, v78, v54
	v_mul_f32_e32 v50, v50, v54
	ds_write_b32 v134, v50 offset:64
	v_add_f32_e32 v50, 1.0, v62
	v_rcp_f32_e32 v50, v50
	v_mul_f32_e32 v54, v55, v63
	v_mul_f32_e32 v55, v51, v58
	v_exp_f32_e32 v55, v55
	v_mul_f32_e32 v50, v79, v50
	v_mul_f32_e32 v50, v54, v50
	ds_write_b32 v134, v50 offset:144
	v_add_f32_e32 v50, 1.0, v55
	v_rcp_f32_e32 v50, v50
	v_mul_f32_e32 v54, 0xbfb8aa3b, v76
	v_mul_f32_e32 v55, v56, v54
	v_exp_f32_e32 v55, v55
	v_mul_f32_e32 v51, v51, v59
	v_mul_f32_e32 v50, v79, v50
	v_mul_f32_e32 v50, v51, v50
	ds_write_b32 v134, v50 offset:208
	v_add_f32_e32 v50, 1.0, v55
	v_rcp_f32_e32 v50, v50
	v_mul_f32_e32 v54, v52, v54
	v_exp_f32_e32 v54, v54
	v_mul_f32_e32 v51, v56, v64
	v_mul_f32_e32 v50, v72, v50
	v_mul_f32_e32 v50, v51, v50
	ds_write_b32 v134, v50 offset:288
	v_add_f32_e32 v50, 1.0, v54
	v_mul_f32_e32 v51, 0xbfb8aa3b, v77
	v_rcp_f32_e32 v50, v50
	v_mul_f32_e32 v54, v57, v51
	v_exp_f32_e32 v54, v54
	v_mul_f32_e32 v51, v53, v51
	v_exp_f32_e32 v51, v51
	v_mul_f32_e32 v52, v52, v60
	v_mul_f32_e32 v50, v72, v50
	v_mul_f32_e32 v50, v52, v50
	v_add_f32_e32 v52, 1.0, v54
	v_rcp_f32_e32 v52, v52
	v_add_f32_e32 v51, 1.0, v51
	v_rcp_f32_e32 v51, v51
	v_cvt_pk_bf16_f32 v68, v70, v71
	v_add_u32_e32 v70, s47, v135
	ds_write_b32 v134, v50 offset:352
	v_mul_f32_e32 v50, v57, v65
	v_mul_f32_e32 v52, v73, v52
	v_mad_i64_i32 v[70:71], s[16:17], v70, s18, v[116:117]
	v_mul_f32_e32 v50, v50, v52
	v_lshl_add_u64 v[70:71], v[70:71], 0, s[12:13]
	ds_write_b32 v114, v50
	v_mul_f32_e32 v50, v53, v61
	v_mul_f32_e32 v51, v73, v51
	v_mul_f32_e32 v50, v50, v51
	v_lshl_add_u64 v[58:59], v[70:71], 0, s[74:75]
	ds_write_b32 v114, v50 offset:64
	v_lshl_add_u64 v[58:59], v[58:59], 0, v[118:119]
	global_store_dwordx4 v[58:59], v[66:69], off nt
	ds_read_b128 v[58:61], v142 offset:576
	ds_read_b128 v[50:53], v141
	ds_read_b128 v[54:57], v141 offset:16
	s_waitcnt lgkmcnt(0)
	v_cvt_pk_bf16_f32 v50, v50, v51
	v_cvt_pk_bf16_f32 v51, v52, v53
	v_mul_f32_e32 v64, 0xbfb8aa3b, v58
	v_cvt_pk_bf16_f32 v53, v56, v57
	v_mul_f32_e32 v56, v38, v64
	v_exp_f32_e32 v65, v56
	v_pk_mul_f32 v[62:63], v[58:59], v[58:59]
	v_mul_f32_e32 v38, v38, v46
	v_mul_f32_e32 v46, v34, v64
	v_add_f32_e32 v58, 1.0, v65
	v_rcp_f32_e32 v58, v58
	v_exp_f32_e32 v46, v46
	v_mul_f32_e32 v34, v34, v42
	v_mul_f32_e32 v42, 0xbfb8aa3b, v59
	v_mul_f32_e32 v58, v62, v58
	v_mul_f32_e32 v38, v38, v58
	ds_write_b32 v134, v38
	v_add_f32_e32 v38, 1.0, v46
	v_rcp_f32_e32 v38, v38
	v_mul_f32_e32 v46, v39, v42
	v_exp_f32_e32 v46, v46
	v_pk_mul_f32 v[56:57], v[60:61], v[60:61]
	v_mul_f32_e32 v38, v62, v38
	v_mul_f32_e32 v34, v34, v38
	ds_write_b32 v134, v34 offset:64
	v_add_f32_e32 v34, 1.0, v46
	v_rcp_f32_e32 v34, v34
	v_mul_f32_e32 v38, v39, v47
	v_mul_f32_e32 v39, v35, v42
	v_exp_f32_e32 v39, v39
	v_mul_f32_e32 v34, v63, v34
	v_mul_f32_e32 v34, v38, v34
	ds_write_b32 v134, v34 offset:144
	v_add_f32_e32 v34, 1.0, v39
	v_rcp_f32_e32 v34, v34
	v_mul_f32_e32 v38, 0xbfb8aa3b, v60
	v_mul_f32_e32 v39, v40, v38
	v_exp_f32_e32 v39, v39
	v_mul_f32_e32 v35, v35, v43
	v_mul_f32_e32 v34, v63, v34
	v_mul_f32_e32 v34, v35, v34
	ds_write_b32 v134, v34 offset:208
	v_add_f32_e32 v34, 1.0, v39
	v_rcp_f32_e32 v34, v34
	v_mul_f32_e32 v38, v36, v38
	v_exp_f32_e32 v38, v38
	v_mul_f32_e32 v35, v40, v48
	v_mul_f32_e32 v34, v56, v34
	v_mul_f32_e32 v34, v35, v34
	ds_write_b32 v134, v34 offset:288
	v_add_f32_e32 v34, 1.0, v38
	v_mul_f32_e32 v35, 0xbfb8aa3b, v61
	v_rcp_f32_e32 v34, v34
	v_mul_f32_e32 v38, v41, v35
	v_exp_f32_e32 v38, v38
	v_mul_f32_e32 v35, v37, v35
	v_exp_f32_e32 v35, v35
	v_mul_f32_e32 v36, v36, v44
	v_mul_f32_e32 v34, v56, v34
	v_mul_f32_e32 v34, v36, v34
	v_add_f32_e32 v36, 1.0, v38
	v_rcp_f32_e32 v36, v36
	v_add_f32_e32 v35, 1.0, v35
	v_rcp_f32_e32 v35, v35
	v_cvt_pk_bf16_f32 v52, v54, v55
	v_add_u32_e32 v54, 0x80, v115
	ds_write_b32 v134, v34 offset:352
	v_mul_f32_e32 v34, v41, v49
	v_mul_f32_e32 v36, v57, v36
	v_mad_i64_i32 v[54:55], s[16:17], v54, s18, v[116:117]
	v_mul_f32_e32 v34, v34, v36
	v_lshl_add_u64 v[54:55], v[54:55], 0, s[12:13]
	ds_write_b32 v114, v34
	v_mul_f32_e32 v34, v37, v45
	v_mul_f32_e32 v35, v57, v35
	v_mul_f32_e32 v34, v34, v35
	v_lshl_add_u64 v[42:43], v[54:55], 0, s[74:75]
	ds_write_b32 v114, v34 offset:64
	v_lshl_add_u64 v[42:43], v[42:43], 0, v[118:119]
	global_store_dwordx4 v[42:43], v[50:53], off nt
	ds_read_b128 v[42:45], v142 offset:640
	ds_read_b128 v[34:37], v141
	ds_read_b128 v[38:41], v141 offset:16
	s_waitcnt lgkmcnt(0)
	v_cvt_pk_bf16_f32 v34, v34, v35
	v_cvt_pk_bf16_f32 v35, v36, v37
	v_mul_f32_e32 v48, 0xbfb8aa3b, v42
	v_cvt_pk_bf16_f32 v37, v40, v41
	v_mul_f32_e32 v40, v22, v48
	v_exp_f32_e32 v49, v40
	v_pk_mul_f32 v[46:47], v[42:43], v[42:43]
	v_mul_f32_e32 v22, v22, v30
	v_mul_f32_e32 v30, v18, v48
	v_add_f32_e32 v42, 1.0, v49
	v_rcp_f32_e32 v42, v42
	v_exp_f32_e32 v30, v30
	v_mul_f32_e32 v18, v18, v26
	v_mul_f32_e32 v26, 0xbfb8aa3b, v43
	v_mul_f32_e32 v42, v46, v42
	v_mul_f32_e32 v22, v22, v42
	ds_write_b32 v134, v22
	v_add_f32_e32 v22, 1.0, v30
	v_rcp_f32_e32 v22, v22
	v_mul_f32_e32 v30, v23, v26
	v_exp_f32_e32 v30, v30
	v_pk_mul_f32 v[40:41], v[44:45], v[44:45]
	v_mul_f32_e32 v22, v46, v22
	v_mul_f32_e32 v18, v18, v22
	ds_write_b32 v134, v18 offset:64
	v_add_f32_e32 v18, 1.0, v30
	v_rcp_f32_e32 v18, v18
	v_mul_f32_e32 v22, v23, v31
	v_mul_f32_e32 v23, v19, v26
	v_exp_f32_e32 v23, v23
	v_mul_f32_e32 v18, v47, v18
	v_mul_f32_e32 v18, v22, v18
	ds_write_b32 v134, v18 offset:144
	v_add_f32_e32 v18, 1.0, v23
	v_rcp_f32_e32 v18, v18
	v_mul_f32_e32 v22, 0xbfb8aa3b, v44
	v_mul_f32_e32 v23, v24, v22
	v_exp_f32_e32 v23, v23
	v_mul_f32_e32 v19, v19, v27
	v_mul_f32_e32 v18, v47, v18
	v_mul_f32_e32 v18, v19, v18
	ds_write_b32 v134, v18 offset:208
	v_add_f32_e32 v18, 1.0, v23
	v_rcp_f32_e32 v18, v18
	v_mul_f32_e32 v22, v20, v22
	v_exp_f32_e32 v22, v22
	v_mul_f32_e32 v19, v24, v32
	v_mul_f32_e32 v18, v40, v18
	v_mul_f32_e32 v18, v19, v18
	ds_write_b32 v134, v18 offset:288
	v_add_f32_e32 v18, 1.0, v22
	v_mul_f32_e32 v19, 0xbfb8aa3b, v45
	v_rcp_f32_e32 v18, v18
	v_mul_f32_e32 v22, v25, v19
	v_exp_f32_e32 v22, v22
	v_mul_f32_e32 v19, v21, v19
	v_exp_f32_e32 v19, v19
	v_mul_f32_e32 v20, v20, v28
	v_mul_f32_e32 v18, v40, v18
	v_mul_f32_e32 v18, v20, v18
	v_add_f32_e32 v20, 1.0, v22
	v_rcp_f32_e32 v20, v20
	v_add_f32_e32 v19, 1.0, v19
	v_rcp_f32_e32 v19, v19
	v_cvt_pk_bf16_f32 v36, v38, v39
	v_add_u32_e32 v38, 0x90, v115
	ds_write_b32 v134, v18 offset:352
	v_mul_f32_e32 v18, v25, v33
	v_mul_f32_e32 v20, v41, v20
	v_mad_i64_i32 v[38:39], s[16:17], v38, s18, v[116:117]
	v_mul_f32_e32 v18, v18, v20
	v_lshl_add_u64 v[38:39], v[38:39], 0, s[12:13]
	ds_write_b32 v114, v18
	v_mul_f32_e32 v18, v21, v29
	v_mul_f32_e32 v19, v41, v19
	v_mul_f32_e32 v18, v18, v19
	v_lshl_add_u64 v[26:27], v[38:39], 0, s[74:75]
	ds_write_b32 v114, v18 offset:64
	v_lshl_add_u64 v[26:27], v[26:27], 0, v[118:119]
	global_store_dwordx4 v[26:27], v[34:37], off nt
	ds_read_b128 v[26:29], v142 offset:704
	ds_read_b128 v[18:21], v141
	ds_read_b128 v[22:25], v141 offset:16
	s_waitcnt lgkmcnt(0)
	v_cvt_pk_bf16_f32 v18, v18, v19
	v_cvt_pk_bf16_f32 v19, v20, v21
	v_mul_f32_e32 v32, 0xbfb8aa3b, v26
	v_cvt_pk_bf16_f32 v21, v24, v25
	v_mul_f32_e32 v24, v6, v32
	v_exp_f32_e32 v33, v24
	v_pk_mul_f32 v[30:31], v[26:27], v[26:27]
	v_mul_f32_e32 v6, v6, v14
	v_mul_f32_e32 v14, v2, v32
	v_add_f32_e32 v26, 1.0, v33
	v_rcp_f32_e32 v26, v26
	v_exp_f32_e32 v14, v14
	v_mul_f32_e32 v2, v2, v10
	v_mul_f32_e32 v10, 0xbfb8aa3b, v27
	v_mul_f32_e32 v26, v30, v26
	v_mul_f32_e32 v6, v6, v26
	ds_write_b32 v134, v6
	v_add_f32_e32 v6, 1.0, v14
	v_rcp_f32_e32 v6, v6
	v_mul_f32_e32 v14, v7, v10
	v_exp_f32_e32 v14, v14
	v_pk_mul_f32 v[24:25], v[28:29], v[28:29]
	v_mul_f32_e32 v6, v30, v6
	v_mul_f32_e32 v2, v2, v6
	ds_write_b32 v134, v2 offset:64
	v_add_f32_e32 v2, 1.0, v14
	v_rcp_f32_e32 v2, v2
	v_mul_f32_e32 v6, v7, v15
	v_mul_f32_e32 v7, v3, v10
	v_exp_f32_e32 v7, v7
	v_mul_f32_e32 v2, v31, v2
	v_mul_f32_e32 v2, v6, v2
	ds_write_b32 v134, v2 offset:144
	v_add_f32_e32 v2, 1.0, v7
	v_rcp_f32_e32 v2, v2
	v_mul_f32_e32 v6, 0xbfb8aa3b, v28
	v_mul_f32_e32 v7, v8, v6
	v_exp_f32_e32 v7, v7
	v_mul_f32_e32 v3, v3, v11
	v_mul_f32_e32 v2, v31, v2
	v_mul_f32_e32 v2, v3, v2
	ds_write_b32 v134, v2 offset:208
	v_add_f32_e32 v2, 1.0, v7
	v_rcp_f32_e32 v2, v2
	v_mul_f32_e32 v6, v4, v6
	v_exp_f32_e32 v6, v6
	v_mul_f32_e32 v3, v8, v16
	v_mul_f32_e32 v2, v24, v2
	v_mul_f32_e32 v2, v3, v2
	ds_write_b32 v134, v2 offset:288
	v_add_f32_e32 v2, 1.0, v6
	v_mul_f32_e32 v3, 0xbfb8aa3b, v29
	v_rcp_f32_e32 v2, v2
	v_mul_f32_e32 v6, v9, v3
	v_exp_f32_e32 v6, v6
	v_mul_f32_e32 v3, v5, v3
	v_exp_f32_e32 v3, v3
	v_mul_f32_e32 v4, v4, v12
	v_mul_f32_e32 v2, v24, v2
	v_mul_f32_e32 v2, v4, v2
	v_add_f32_e32 v4, 1.0, v6
	v_rcp_f32_e32 v4, v4
	v_add_f32_e32 v3, 1.0, v3
	v_rcp_f32_e32 v3, v3
	ds_write_b32 v134, v2 offset:352
	v_mul_f32_e32 v2, v9, v17
	v_mul_f32_e32 v4, v25, v4
	v_mul_f32_e32 v2, v2, v4
	ds_write_b32 v114, v2
	v_mul_f32_e32 v2, v5, v13
	v_mul_f32_e32 v3, v25, v3
	v_mul_f32_e32 v2, v2, v3
	ds_write_b32 v114, v2 offset:64
	ds_read_b128 v[2:5], v141
	ds_read_b128 v[6:9], v141 offset:16
	v_cvt_pk_bf16_f32 v20, v22, v23
	v_add_u32_e32 v22, 0xa0, v115
	s_waitcnt lgkmcnt(0)
	v_cvt_pk_bf16_f32 v2, v2, v3
	v_cvt_pk_bf16_f32 v3, v4, v5
	v_cvt_pk_bf16_f32 v4, v6, v7
	v_add_u32_e32 v6, 0xb0, v115
	v_mad_i64_i32 v[22:23], s[16:17], v22, s18, v[116:117]
	v_mad_i64_i32 v[6:7], s[16:17], v6, s18, v[116:117]
	v_lshl_add_u64 v[22:23], v[22:23], 0, s[12:13]
	v_lshl_add_u64 v[6:7], v[6:7], 0, s[12:13]
	v_lshl_add_u64 v[10:11], v[22:23], 0, s[74:75]
	v_lshl_add_u64 v[6:7], v[6:7], 0, s[74:75]
	v_lshl_add_u64 v[10:11], v[10:11], 0, v[118:119]
	v_lshl_add_u64 v[6:7], v[6:7], 0, v[118:119]
	s_and_b64 vcc, exec, s[14:15]
	global_store_dwordx4 v[10:11], v[18:21], off nt
	v_cvt_pk_bf16_f32 v5, v8, v9
	global_store_dwordx4 v[6:7], v[2:5], off nt
	s_waitcnt vmcnt(24)
	v_add_f32_e32 v164, v160, v161
	v_add_f32_e32 v164, v162, v164
	v_add_f32_e32 v164, v163, v164
	v_fmamk_f32 v164, v164, 0x3a800000, v208
	v_mul_f32_e32 v165, 0x4b800000, v164
	v_cmp_gt_f32_e64 s[12:13], s95, v164
	s_nop 1
	v_cndmask_b32_e64 v164, v164, v165, s[12:13]
	v_rsq_f32_e32 v164, v164
	s_nop 0
	v_mul_f32_e32 v165, 0x45800000, v164
	v_cndmask_b32_e64 v252, v164, v165, s[12:13]
	s_barrier
	s_cbranch_vccnz .LBB0_474
